# adaLN GEMV loop: the 15 follow-up row loads are issued before the wait for the first one (vmcnt(15) instead of vmcnt(0))
# baseline (speedup 1.0000x reference)
; __device__ __forceinline__ void p0_ada_item(Frame& F, int item, LAS float* sil) {
;     ...
;     const float* wp = F.w_ada + (size_t)k0 * NMODC + 192 * s + 3 * lane;
; #pragma unroll 16
;     for (int kk = 0; kk < 256; ++kk) { const f32x3 w = *(const f32x3*)(wp + (size_t)kk * NMODC);
; #pragma unroll
;         for (int r = 0; r < 5; ++r) acc[r] += w * sil[r * 256 + kk]; }
.LBB0_8:
	v_lshl_add_u64 v[46:47], v[44:45], 0, s[0:1]
	v_add_co_u32_e32 v112, vcc, s5, v46
	global_load_dwordx3 v[108:110], v[46:47], off
	s_nop 0
	v_addc_co_u32_e32 v113, vcc, 0, v47, vcc
	v_add_co_u32_e32 v116, vcc, s7, v46
	v_mov_b32_e32 v1, s6
	s_nop 0
	v_addc_co_u32_e32 v117, vcc, 0, v47, vcc
	v_add_co_u32_e32 v120, vcc, s10, v46
	ds_read_b128 v[48:51], v1
	ds_read_b128 v[52:55], v1 offset:16
	v_addc_co_u32_e32 v121, vcc, 0, v47, vcc
	v_add_co_u32_e32 v124, vcc, s11, v46
	ds_read_b128 v[56:59], v1 offset:1024
	ds_read_b128 v[60:63], v1 offset:1040
	ds_read_b128 v[64:67], v1 offset:2048
	ds_read_b128 v[68:71], v1 offset:2064
	ds_read_b128 v[72:75], v1 offset:3072
	ds_read_b128 v[76:79], v1 offset:3088
	ds_read_b128 v[80:83], v1 offset:4096
	ds_read_b128 v[84:87], v1 offset:4112
	ds_read_b128 v[88:91], v1 offset:32
	ds_read_b128 v[2:5], v1 offset:48
	v_addc_co_u32_e32 v125, vcc, 0, v47, vcc
	v_add_co_u32_e32 v128, vcc, s12, v46
	ds_read_b128 v[92:95], v1 offset:1056
	ds_read_b128 v[18:21], v1 offset:1072
	ds_read_b128 v[96:99], v1 offset:2080
	ds_read_b128 v[14:17], v1 offset:2096
	ds_read_b128 v[100:103], v1 offset:3104
	ds_read_b128 v[10:13], v1 offset:3120
	ds_read_b128 v[104:107], v1 offset:4128
	ds_read_b128 v[6:9], v1 offset:4144
	v_addc_co_u32_e32 v129, vcc, 0, v47, vcc
	v_add_co_u32_e32 v132, vcc, s13, v46
	s_add_i32 s6, s6, 64
	s_nop 0
	v_addc_co_u32_e32 v133, vcc, 0, v47, vcc
	v_add_co_u32_e32 v136, vcc, s14, v46
	s_add_u32 s0, s0, 0x180000
	s_nop 0
	v_addc_co_u32_e32 v137, vcc, 0, v47, vcc
	v_add_co_u32_e32 v140, vcc, s15, v46
	s_addc_u32 s1, s1, 0
	s_nop 0
	v_addc_co_u32_e32 v141, vcc, 0, v47, vcc
	v_add_co_u32_e32 v144, vcc, s16, v46
	s_cmp_lg_u32 s0, 0x1800000
	s_nop 0
	v_addc_co_u32_e32 v145, vcc, 0, v47, vcc
	v_add_co_u32_e32 v148, vcc, s17, v46
	s_nop 1
	v_addc_co_u32_e32 v149, vcc, 0, v47, vcc
	v_add_co_u32_e32 v152, vcc, s18, v46
	s_nop 1
	v_addc_co_u32_e32 v153, vcc, 0, v47, vcc
	v_add_co_u32_e32 v156, vcc, s19, v46
	s_nop 1
	v_addc_co_u32_e32 v157, vcc, 0, v47, vcc
	v_add_co_u32_e32 v160, vcc, s20, v46
	s_nop 1
	v_addc_co_u32_e32 v161, vcc, 0, v47, vcc
	v_add_co_u32_e32 v164, vcc, s21, v46
	s_nop 1
	v_addc_co_u32_e32 v165, vcc, 0, v47, vcc
	v_add_co_u32_e32 v46, vcc, s22, v46
	s_nop 1
	v_addc_co_u32_e32 v47, vcc, 0, v47, vcc
	global_load_dwordx3 v[112:114], v[112:113], off
	s_nop 0
	global_load_dwordx3 v[116:118], v[116:117], off
	s_nop 0
	global_load_dwordx3 v[120:122], v[120:121], off
	s_nop 0
	global_load_dwordx3 v[124:126], v[124:125], off
	s_nop 0
	global_load_dwordx3 v[128:130], v[128:129], off
	s_nop 0
	global_load_dwordx3 v[132:134], v[132:133], off
	s_nop 0
	global_load_dwordx3 v[136:138], v[136:137], off
	s_nop 0
	global_load_dwordx3 v[140:142], v[140:141], off
	s_nop 0
	global_load_dwordx3 v[144:146], v[144:145], off
	s_nop 0
	global_load_dwordx3 v[148:150], v[148:149], off
	s_nop 0
	global_load_dwordx3 v[152:154], v[152:153], off
	s_nop 0
	global_load_dwordx3 v[156:158], v[156:157], off
	s_nop 0
	global_load_dwordx3 v[160:162], v[160:161], off
	s_nop 0
	global_load_dwordx3 v[164:166], v[164:165], off
	s_nop 0
	global_load_dwordx3 v[168:170], v[46:47], off
	s_waitcnt vmcnt(15) lgkmcnt(14)
	v_fmac_f32_e32 v38, v108, v48
	v_fmac_f32_e32 v39, v109, v48
	v_fmac_f32_e32 v40, v110, v48
	v_fmac_f32_e32 v34, v108, v56
	v_fmac_f32_e32 v35, v109, v56
	v_fmac_f32_e32 v36, v110, v56
	v_fmac_f32_e32 v30, v108, v64
	v_fmac_f32_e32 v31, v109, v64
	v_fmac_f32_e32 v32, v110, v64
	s_waitcnt lgkmcnt(13)
	v_fmac_f32_e32 v26, v108, v72
	v_fmac_f32_e32 v27, v109, v72
	v_fmac_f32_e32 v28, v110, v72
	s_waitcnt lgkmcnt(11)
	v_fmac_f32_e32 v25, v108, v80
	v_fmac_f32_e32 v23, v109, v80
	v_fmac_f32_e32 v24, v110, v80
	s_waitcnt vmcnt(14)
	v_fmac_f32_e32 v40, v114, v49
	v_fmac_f32_e32 v39, v113, v49
	v_fmac_f32_e32 v38, v112, v49
	v_fmac_f32_e32 v36, v114, v57
	v_fmac_f32_e32 v35, v113, v57
	v_fmac_f32_e32 v34, v112, v57
	v_fmac_f32_e32 v32, v114, v65
	v_fmac_f32_e32 v31, v113, v65
	v_fmac_f32_e32 v30, v112, v65
	v_fmac_f32_e32 v28, v114, v73
	v_fmac_f32_e32 v27, v113, v73
	v_fmac_f32_e32 v26, v112, v73
	v_fmac_f32_e32 v24, v114, v81
	v_fmac_f32_e32 v23, v113, v81
	v_fmac_f32_e32 v25, v112, v81
	s_waitcnt vmcnt(13)
	v_fmac_f32_e32 v38, v116, v50
	v_fmac_f32_e32 v39, v117, v50
	v_fmac_f32_e32 v40, v118, v50
	v_fmac_f32_e32 v34, v116, v58
	v_fmac_f32_e32 v35, v117, v58
	v_fmac_f32_e32 v36, v118, v58
	v_fmac_f32_e32 v30, v116, v66
	v_fmac_f32_e32 v31, v117, v66
	v_fmac_f32_e32 v32, v118, v66
	v_fmac_f32_e32 v26, v116, v74
	v_fmac_f32_e32 v27, v117, v74
	v_fmac_f32_e32 v28, v118, v74
	v_fmac_f32_e32 v25, v116, v82
	v_fmac_f32_e32 v23, v117, v82
	v_fmac_f32_e32 v24, v118, v82
	s_waitcnt vmcnt(12)
	v_fmac_f32_e32 v40, v122, v51
	v_fmac_f32_e32 v39, v121, v51
	v_fmac_f32_e32 v38, v120, v51
	v_fmac_f32_e32 v36, v122, v59
	v_fmac_f32_e32 v35, v121, v59
	v_fmac_f32_e32 v34, v120, v59
	v_fmac_f32_e32 v32, v122, v67
	v_fmac_f32_e32 v31, v121, v67
	v_fmac_f32_e32 v30, v120, v67
	v_fmac_f32_e32 v28, v122, v75
	v_fmac_f32_e32 v27, v121, v75
	v_fmac_f32_e32 v26, v120, v75
	v_fmac_f32_e32 v24, v122, v83
	v_fmac_f32_e32 v23, v121, v83
	v_fmac_f32_e32 v25, v120, v83
	s_waitcnt vmcnt(11)
	v_fmac_f32_e32 v38, v124, v52
	v_fmac_f32_e32 v39, v125, v52
	v_fmac_f32_e32 v40, v126, v52
	v_fmac_f32_e32 v34, v124, v60
	v_fmac_f32_e32 v35, v125, v60
	v_fmac_f32_e32 v36, v126, v60
	v_fmac_f32_e32 v30, v124, v68
	v_fmac_f32_e32 v31, v125, v68
	v_fmac_f32_e32 v32, v126, v68
	v_fmac_f32_e32 v26, v124, v76
	v_fmac_f32_e32 v27, v125, v76
	v_fmac_f32_e32 v28, v126, v76
	s_waitcnt lgkmcnt(10)
	v_fmac_f32_e32 v25, v124, v84
	v_fmac_f32_e32 v23, v125, v84
	v_fmac_f32_e32 v24, v126, v84
	s_waitcnt vmcnt(10)
; __device__ __forceinline__ void p0_ada_item(Frame& F, int item, LAS float* sil) {
;     ...
;     const float* wp = F.w_ada + (size_t)k0 * NMODC + 192 * s + 3 * lane;
; #pragma unroll 16
;     for (int kk = 0; kk < 256; ++kk) { const f32x3 w = *(const f32x3*)(wp + (size_t)kk * NMODC);
; #pragma unroll
;         for (int r = 0; r < 5; ++r) acc[r] += w * sil[r * 256 + kk]; }
; #pragma unroll
;     for (int r = 0; r < 5; ++r) *(f32x3*)(F.part + (size_t)(ks * 5 + r) * NMODC + 192 * s + 3 * lane) = acc[r];
	v_fmac_f32_e32 v40, v130, v53
	v_fmac_f32_e32 v39, v129, v53
	v_fmac_f32_e32 v38, v128, v53
	v_fmac_f32_e32 v36, v130, v61
	v_fmac_f32_e32 v35, v129, v61
	v_fmac_f32_e32 v34, v128, v61
	v_fmac_f32_e32 v32, v130, v69
	v_fmac_f32_e32 v31, v129, v69
	v_fmac_f32_e32 v30, v128, v69
	v_fmac_f32_e32 v28, v130, v77
	v_fmac_f32_e32 v27, v129, v77
	v_fmac_f32_e32 v26, v128, v77
	v_fmac_f32_e32 v24, v130, v85
	v_fmac_f32_e32 v23, v129, v85
	v_fmac_f32_e32 v25, v128, v85
	s_waitcnt vmcnt(9)
	v_fmac_f32_e32 v38, v132, v54
	v_fmac_f32_e32 v39, v133, v54
	v_fmac_f32_e32 v40, v134, v54
	v_fmac_f32_e32 v34, v132, v62
	v_fmac_f32_e32 v35, v133, v62
	v_fmac_f32_e32 v36, v134, v62
	v_fmac_f32_e32 v30, v132, v70
	v_fmac_f32_e32 v31, v133, v70
	v_fmac_f32_e32 v32, v134, v70
	v_fmac_f32_e32 v26, v132, v78
	v_fmac_f32_e32 v27, v133, v78
	v_fmac_f32_e32 v28, v134, v78
	v_fmac_f32_e32 v25, v132, v86
	v_fmac_f32_e32 v23, v133, v86
	v_fmac_f32_e32 v24, v134, v86
	s_waitcnt vmcnt(8)
	v_fmac_f32_e32 v40, v138, v55
	v_fmac_f32_e32 v39, v137, v55
	v_fmac_f32_e32 v38, v136, v55
	v_fmac_f32_e32 v36, v138, v63
	v_fmac_f32_e32 v35, v137, v63
	v_fmac_f32_e32 v34, v136, v63
	v_fmac_f32_e32 v32, v138, v71
	v_fmac_f32_e32 v31, v137, v71
	v_fmac_f32_e32 v30, v136, v71
	v_fmac_f32_e32 v28, v138, v79
	v_fmac_f32_e32 v27, v137, v79
	v_fmac_f32_e32 v26, v136, v79
	v_fmac_f32_e32 v24, v138, v87
	v_fmac_f32_e32 v23, v137, v87
	v_fmac_f32_e32 v25, v136, v87
	s_waitcnt vmcnt(7) lgkmcnt(9)
	v_fmac_f32_e32 v38, v140, v88
	v_fmac_f32_e32 v39, v141, v88
	v_fmac_f32_e32 v40, v142, v88
	s_waitcnt lgkmcnt(7)
	v_fmac_f32_e32 v34, v140, v92
	v_fmac_f32_e32 v35, v141, v92
	v_fmac_f32_e32 v36, v142, v92
	s_waitcnt lgkmcnt(5)
	v_fmac_f32_e32 v30, v140, v96
	v_fmac_f32_e32 v31, v141, v96
	v_fmac_f32_e32 v32, v142, v96
	s_waitcnt lgkmcnt(3)
	v_fmac_f32_e32 v26, v140, v100
	v_fmac_f32_e32 v27, v141, v100
	v_fmac_f32_e32 v28, v142, v100
	s_waitcnt lgkmcnt(1)
	v_fmac_f32_e32 v25, v140, v104
	v_fmac_f32_e32 v23, v141, v104
	v_fmac_f32_e32 v24, v142, v104
	s_waitcnt vmcnt(6)
	v_fmac_f32_e32 v40, v146, v89
	v_fmac_f32_e32 v39, v145, v89
	v_fmac_f32_e32 v38, v144, v89
	v_fmac_f32_e32 v36, v146, v93
	v_fmac_f32_e32 v35, v145, v93
	v_fmac_f32_e32 v34, v144, v93
	v_fmac_f32_e32 v32, v146, v97
	v_fmac_f32_e32 v31, v145, v97
	v_fmac_f32_e32 v30, v144, v97
	v_fmac_f32_e32 v28, v146, v101
	v_fmac_f32_e32 v27, v145, v101
	v_fmac_f32_e32 v26, v144, v101
	v_fmac_f32_e32 v24, v146, v105
	v_fmac_f32_e32 v23, v145, v105
	v_fmac_f32_e32 v25, v144, v105
	s_waitcnt vmcnt(5)
	v_fmac_f32_e32 v38, v148, v90
	v_fmac_f32_e32 v39, v149, v90
	v_fmac_f32_e32 v40, v150, v90
	v_fmac_f32_e32 v34, v148, v94
	v_fmac_f32_e32 v35, v149, v94
	v_fmac_f32_e32 v36, v150, v94
	v_fmac_f32_e32 v30, v148, v98
	v_fmac_f32_e32 v31, v149, v98
	v_fmac_f32_e32 v32, v150, v98
	v_fmac_f32_e32 v26, v148, v102
	v_fmac_f32_e32 v27, v149, v102
	v_fmac_f32_e32 v28, v150, v102
	v_fmac_f32_e32 v25, v148, v106
	v_fmac_f32_e32 v23, v149, v106
	v_fmac_f32_e32 v24, v150, v106
	s_waitcnt vmcnt(4)
	v_fmac_f32_e32 v40, v154, v91
	v_fmac_f32_e32 v39, v153, v91
	v_fmac_f32_e32 v38, v152, v91
	v_fmac_f32_e32 v36, v154, v95
	v_fmac_f32_e32 v35, v153, v95
	v_fmac_f32_e32 v34, v152, v95
	v_fmac_f32_e32 v32, v154, v99
	v_fmac_f32_e32 v31, v153, v99
	v_fmac_f32_e32 v30, v152, v99
	v_fmac_f32_e32 v28, v154, v103
	v_fmac_f32_e32 v27, v153, v103
	v_fmac_f32_e32 v26, v152, v103
	v_fmac_f32_e32 v24, v154, v107
	v_fmac_f32_e32 v23, v153, v107
	v_fmac_f32_e32 v25, v152, v107
	s_waitcnt vmcnt(3)
	v_fmac_f32_e32 v38, v156, v2
	v_fmac_f32_e32 v39, v157, v2
	v_fmac_f32_e32 v40, v158, v2
	v_fmac_f32_e32 v34, v156, v18
	v_fmac_f32_e32 v35, v157, v18
	v_fmac_f32_e32 v36, v158, v18
	v_fmac_f32_e32 v30, v156, v14
	v_fmac_f32_e32 v31, v157, v14
	v_fmac_f32_e32 v32, v158, v14
	v_fmac_f32_e32 v26, v156, v10
	v_fmac_f32_e32 v27, v157, v10
	v_fmac_f32_e32 v28, v158, v10
	s_waitcnt lgkmcnt(0)
	v_fmac_f32_e32 v25, v156, v6
	v_fmac_f32_e32 v23, v157, v6
	v_fmac_f32_e32 v24, v158, v6
	s_waitcnt vmcnt(2)
	v_fmac_f32_e32 v40, v162, v3
	v_fmac_f32_e32 v39, v161, v3
	v_fmac_f32_e32 v38, v160, v3
	v_fmac_f32_e32 v36, v162, v19
	v_fmac_f32_e32 v35, v161, v19
	v_fmac_f32_e32 v34, v160, v19
	v_fmac_f32_e32 v32, v162, v15
	v_fmac_f32_e32 v31, v161, v15
	v_fmac_f32_e32 v30, v160, v15
	v_fmac_f32_e32 v28, v162, v11
	v_fmac_f32_e32 v27, v161, v11
	v_fmac_f32_e32 v26, v160, v11
	v_fmac_f32_e32 v24, v162, v7
	v_fmac_f32_e32 v23, v161, v7
	v_fmac_f32_e32 v25, v160, v7
	s_waitcnt vmcnt(1)
	v_fmac_f32_e32 v38, v164, v4
	v_fmac_f32_e32 v39, v165, v4
	v_fmac_f32_e32 v40, v166, v4
	v_fmac_f32_e32 v34, v164, v20
	v_fmac_f32_e32 v35, v165, v20
	v_fmac_f32_e32 v36, v166, v20
	v_fmac_f32_e32 v30, v164, v16
	v_fmac_f32_e32 v31, v165, v16
	v_fmac_f32_e32 v32, v166, v16
	v_fmac_f32_e32 v26, v164, v12
	v_fmac_f32_e32 v27, v165, v12
	v_fmac_f32_e32 v28, v166, v12
	v_fmac_f32_e32 v25, v164, v8
	v_fmac_f32_e32 v23, v165, v8
	v_fmac_f32_e32 v24, v166, v8
	s_waitcnt vmcnt(0)
	v_fmac_f32_e32 v40, v170, v5
	v_fmac_f32_e32 v39, v169, v5
	v_fmac_f32_e32 v38, v168, v5
	v_fmac_f32_e32 v36, v170, v21
	v_fmac_f32_e32 v35, v169, v21
	v_fmac_f32_e32 v34, v168, v21
	v_fmac_f32_e32 v32, v170, v17
	v_fmac_f32_e32 v31, v169, v17
	v_fmac_f32_e32 v30, v168, v17
	v_fmac_f32_e32 v28, v170, v13
	v_fmac_f32_e32 v27, v169, v13
	v_fmac_f32_e32 v26, v168, v13
	v_fmac_f32_e32 v24, v170, v9
	v_fmac_f32_e32 v23, v169, v9
	v_fmac_f32_e32 v25, v168, v9
	s_cbranch_scc1 .LBB0_8
	s_mul_i32 s5, s2, 5
	s_mul_i32 s2, s2, 0x78000
	s_mul_hi_i32 s0, s5, 0x18000
	s_add_u32 s1, s86, s2
	s_addc_u32 s6, s87, s0
	s_lshl_b32 s4, s4, 2
	s_add_u32 s0, s1, s4
	s_addc_u32 s1, s6, 0
	v_lshlrev_b32_e32 v1, 2, v42
	global_store_dwordx3 v1, v[38:40], s[0:1]
	s_add_i32 s0, s5, 1
	s_add_i32 s1, s2, 0x18000
	s_mul_hi_i32 s0, s0, 0x18000
	s_add_u32 s1, s86, s1
	s_addc_u32 s6, s87, s0
	s_add_u32 s0, s1, s4
	s_addc_u32 s1, s6, 0
	global_store_dwordx3 v1, v[34:36], s[0:1]
	s_add_i32 s0, s5, 2
	s_add_i32 s1, s2, 0x30000
	s_mul_hi_i32 s0, s0, 0x18000
	s_add_u32 s1, s86, s1
	s_addc_u32 s6, s87, s0
	s_add_u32 s0, s1, s4
	s_addc_u32 s1, s6, 0
	global_store_dwordx3 v1, v[30:32], s[0:1]
	s_add_i32 s0, s5, 3
	s_add_i32 s1, s2, 0x48000
	s_mul_hi_i32 s0, s0, 0x18000
	s_add_u32 s1, s86, s1
	s_addc_u32 s6, s87, s0
	s_add_u32 s0, s1, s4
	s_addc_u32 s1, s6, 0
	s_add_i32 s5, s5, 4
	s_add_i32 s2, s2, 0x60000
	global_store_dwordx3 v1, v[26:28], s[0:1]
	s_mul_hi_i32 s0, s5, 0x18000
	s_add_u32 s1, s86, s2
	s_addc_u32 s2, s87, s0
	s_add_u32 s0, s1, s4
	v_mov_b32_e32 v22, v25
	s_addc_u32 s1, s2, 0
	global_store_dwordx3 v1, v[22:24], s[0:1]
	s_waitcnt lgkmcnt(0)
